# GEMM phase prologue: all 14 LDS-DMA fill loads issued before the first wait/barrier (one round trip instead of two)
# speedup vs baseline: 1.0184x; 1.0184x over previous
.LBB0_163:
	v_lshrrev_b32_e32 v16, 1, v14
	v_and_b32_e32 v16, 24, v16
	s_lshl_b32 s29, s29, 5
	v_and_b32_e32 v15, 15, v14
	v_lshlrev_b32_e32 v17, 1, v16
	v_lshlrev_b32_e32 v14, 2, v14
	s_and_b32 s38, s29, 0x60
	v_lshl_or_b32 v3, s36, 6, v15
	v_lshl_or_b32 v15, v15, 6, v17
	s_lshl_b32 s36, s36, 13
	v_and_b32_e32 v14, 32, v14
	s_lshl_b32 s29, s38, 7
	v_bitop3_b32 v17, v15, s36, v14 bitop3:0xde
	s_add_u32 s36, s34, 0x160000
	v_mov_b32_e32 v135, v2
	s_addc_u32 s37, s35, 0
	v_mov_b32_e32 v1, v2
	v_bitop3_b32 v142, v15, s29, v14 bitop3:0xde
	s_add_i32 m0, s57, 0x18000
	v_lshl_add_u64 v[14:15], s[36:37], 0, v[134:135]
	global_load_lds_dwordx4 v[14:15], off
	v_lshl_add_u64 v[14:15], s[36:37], 0, v[0:1]
	s_add_i32 m0, s57, 0x1a000
	s_add_i32 s61, s57, 0x8000
	s_add_i32 s62, s57, 0xa000
	global_load_lds_dwordx4 v[14:15], off
	v_lshl_add_u64 v[4:5], v[4:5], 0, s[14:15]
	s_mov_b32 m0, s61
	s_add_u32 s36, s34, 0x164000
	global_load_lds_dwordx4 v[4:5], off
	v_lshl_add_u64 v[4:5], v[6:7], 0, s[14:15]
	s_mov_b32 m0, s62
	s_addc_u32 s37, s35, 0
	global_load_lds_dwordx4 v[4:5], off
	s_add_i32 m0, s57, 0x1c000
	v_lshl_add_u64 v[4:5], s[36:37], 0, v[134:135]
	global_load_lds_dwordx4 v[4:5], off
	v_lshl_add_u64 v[4:5], s[36:37], 0, v[0:1]
	s_add_i32 m0, s57, 0x1e000
	s_cmpk_lt_u32 s28, 0x100
	global_load_lds_dwordx4 v[4:5], off
	s_waitcnt vmcnt(8)
	s_barrier
	v_lshlrev_b32_e32 v4, 15, v12
	v_and_b32_e32 v4, 0xffff0000, v4
	v_lshl_add_u32 v4, v11, 12, v4
	v_and_b32_e32 v5, 1, v12
	v_lshl_or_b32 v4, v5, 6, v4
	v_lshl_add_u32 v138, v13, 1, v4
	v_lshlrev_b32_e32 v4, 15, v8
	v_and_b32_e32 v4, 0xffff0000, v4
	s_waitcnt vmcnt(6)
	v_lshl_add_u32 v4, v9, 12, v4
	v_and_b32_e32 v5, 1, v8
	v_lshl_or_b32 v4, v5, 6, v4
	v_readlane_b32 s36, v241, 60
	s_cselect_b64 s[28:29], -1, 0
	v_or_b32_e32 v143, s38, v16
	v_mov_b32_e32 v139, v2
	v_lshl_add_u32 v140, v10, 1, v4
	v_mov_b32_e32 v141, v2
	s_mov_b32 s63, 0
	v_add_u32_e32 v144, 0, v17
	v_readlane_b32 s64, v241, 50
	s_mov_b32 s69, s36
	s_barrier
	v_readlane_b32 s37, v241, 61
	s_branch .LBB0_166

.LBB0_237:
	v_bfe_u32 v16, v14, 4, 2
	v_and_b32_e32 v15, 15, v14
	v_lshlrev_b32_e32 v18, 4, v16
	v_lshlrev_b32_e32 v14, 2, v14
	s_and_b32 s37, s27, 3
	v_lshl_or_b32 v3, s26, 6, v15
	v_lshl_or_b32 v15, v15, 6, v18
	s_lshl_b32 s26, s26, 13
	v_and_b32_e32 v14, 32, v14
	v_bitop3_b32 v18, v15, s26, v14 bitop3:0xde
	s_lshl_b32 s26, s37, 12
	v_bitop3_b32 v155, v15, s26, v14 bitop3:0xde
	s_add_u32 s26, s24, 0x200000
	s_addc_u32 s27, s25, 0
	s_add_u32 s28, s34, 0x70000
	v_mov_b32_e32 v151, v2
	s_addc_u32 s29, s35, 0
	v_mov_b32_e32 v1, v2
	s_add_i32 m0, s69, 0x18000
	v_lshl_add_u64 v[14:15], s[28:29], 0, v[150:151]
	global_load_lds_dwordx4 v[14:15], off
	v_lshl_add_u64 v[14:15], s[28:29], 0, v[0:1]
	s_add_i32 m0, s69, 0x1a000
	s_add_i32 s97, s69, 0x8000
	s_add_i32 s76, s69, 0xa000
	global_load_lds_dwordx4 v[14:15], off
	v_lshl_add_u64 v[4:5], v[4:5], 0, s[14:15]
	s_mov_b32 m0, s97
	s_add_u32 s28, s34, 0x74000
	global_load_lds_dwordx4 v[4:5], off
	v_lshl_add_u64 v[4:5], v[6:7], 0, s[14:15]
	s_mov_b32 m0, s76
	s_addc_u32 s29, s35, 0
	global_load_lds_dwordx4 v[4:5], off
	s_add_i32 m0, s69, 0x1c000
	v_lshl_add_u64 v[4:5], s[28:29], 0, v[150:151]
	global_load_lds_dwordx4 v[4:5], off
	v_lshl_add_u64 v[4:5], s[28:29], 0, v[0:1]
	s_add_i32 m0, s69, 0x1e000
	v_lshlrev_b32_e32 v17, 3, v16
	global_load_lds_dwordx4 v[4:5], off
	s_waitcnt vmcnt(8)
	s_barrier
	v_lshlrev_b32_e32 v4, 15, v12
	v_and_b32_e32 v4, 0xffff0000, v4
	v_lshl_add_u32 v4, v11, 12, v4
	v_and_b32_e32 v5, 1, v12
	v_lshl_or_b32 v4, v5, 6, v4
	v_lshl_add_u32 v172, v13, 1, v4
	v_lshlrev_b32_e32 v4, 15, v8
	v_and_b32_e32 v4, 0xffff0000, v4
	s_waitcnt vmcnt(6)
	s_cmpk_lt_u32 s36, 0x100
	v_lshl_add_u32 v4, v9, 12, v4
	v_and_b32_e32 v5, 1, v8
	s_cselect_b64 s[28:29], -1, 0
	v_lshl_or_b32 v154, s37, 5, v17
	s_bitcmp0_b32 s36, 6
	v_lshl_or_b32 v4, v5, 6, v4
	v_readlane_b32 s36, v240, 0
	s_mov_b32 s77, 0
	s_cselect_b64 s[50:51], -1, 0
	v_cmp_gt_u32_e64 s[38:39], 2, v16
	v_cmp_eq_u32_e64 s[40:41], 0, v16
	v_mov_b32_e32 v173, v2
	v_lshl_add_u32 v174, v10, 1, v4
	v_mov_b32_e32 v175, v2
	v_add_u32_e32 v181, 0, v18
	v_readlane_b32 s64, v241, 54
	s_mov_b32 s62, s36
	s_barrier
	v_readlane_b32 s37, v240, 1
	s_branch .LBB0_240

.LBB0_547:
	v_bfe_u32 v16, v14, 4, 2
	v_and_b32_e32 v15, 15, v14
	v_lshlrev_b32_e32 v18, 4, v16
	v_lshlrev_b32_e32 v14, 2, v14
	s_and_b32 s63, s39, 3
	s_lshr_b32 s69, s37, 6
	v_lshl_or_b32 v3, s38, 6, v15
	v_lshl_or_b32 v15, v15, 6, v18
	s_lshl_b32 s37, s38, 13
	v_and_b32_e32 v14, 32, v14
	s_lshl_b32 s64, s70, 19
	v_bitop3_b32 v18, v15, s37, v14 bitop3:0xde
	s_lshl_b32 s37, s63, 12
	s_lshl_b64 s[38:39], s[64:65], 2
	s_add_u32 s24, s24, s38
	s_addc_u32 s25, s25, s39
	s_add_u32 s24, s24, 0x22800000
	s_addc_u32 s25, s25, 0
	s_add_u32 s38, s34, 0x40000
	v_mov_b32_e32 v175, v2
	s_addc_u32 s39, s35, 0
	v_mov_b32_e32 v1, v2
	v_bitop3_b32 v200, v15, s37, v14 bitop3:0xde
	s_add_i32 m0, s59, 0x18000
	v_lshl_add_u64 v[14:15], s[38:39], 0, v[174:175]
	global_load_lds_dwordx4 v[14:15], off
	v_lshl_add_u64 v[14:15], s[38:39], 0, v[0:1]
	s_add_i32 m0, s59, 0x1a000
	s_add_i32 s71, s59, 0x8000
	s_add_i32 s76, s59, 0xa000
	global_load_lds_dwordx4 v[14:15], off
	v_lshl_add_u64 v[4:5], v[4:5], 0, s[14:15]
	s_mov_b32 m0, s71
	s_add_u32 s38, s34, 0x44000
	global_load_lds_dwordx4 v[4:5], off
	v_lshl_add_u64 v[4:5], v[6:7], 0, s[14:15]
	s_mov_b32 m0, s76
	s_addc_u32 s39, s35, 0
	global_load_lds_dwordx4 v[4:5], off
	s_add_i32 m0, s59, 0x1c000
	v_lshl_add_u64 v[4:5], s[38:39], 0, v[174:175]
	global_load_lds_dwordx4 v[4:5], off
	v_lshl_add_u64 v[4:5], s[38:39], 0, v[0:1]
	s_add_i32 m0, s59, 0x1e000
	s_add_i32 s77, s69, -2
	global_load_lds_dwordx4 v[4:5], off
	s_waitcnt vmcnt(8)
	s_barrier
	v_add_u32_e32 v4, v13, v11
	v_add_lshl_u32 v4, v4, v12, 1
	v_mov_b32_e32 v5, v2
	s_waitcnt vmcnt(6)
	v_lshl_add_u64 v[178:179], s[26:27], 0, v[4:5]
	v_add_u32_e32 v4, v10, v8
	v_lshlrev_b32_e32 v17, 3, v16
	s_cmpk_lt_u32 s36, 0x100
	v_add_lshl_u32 v4, v4, v9, 1
	s_mov_b32 s1, s0
	s_mov_b32 s44, s0
	s_mov_b32 s45, s0
	v_lshl_or_b32 v201, s63, 5, v17
	s_cselect_b64 s[46:47], -1, 0
	s_mov_b32 s88, 0
	v_cmp_eq_u32_e64 s[38:39], 0, v16
	v_lshl_add_u64 v[180:181], s[26:27], 0, v[4:5]
	v_add_u32_e32 v202, 0, v18
	v_readlane_b32 s64, v241, 57
	v_readlane_b32 s96, v241, 53
	s_barrier
	s_branch .LBB0_550
